# ssm phases: parameter and B-matrix loads of the per-task set-up issued together with the first loads (fewer serialized memory round trips)
# speedup vs baseline: 1.0111x; 1.0048x over previous
; #define LAS __attribute__((address_space(3)))
; template <bool PASSC>
; __device__ __forceinline__ void ssm_task_old(int task, const SsmW& W, const bf16_t* U, f32x2* SST, bf16_t* YS, LAS unsigned char* wl, int lane) {
;     const int c = task & 127, g = (task >> 7) & 15, b = task >> 11;
;     const size_t tok0 = (size_t)b * SEQ + c * 64;
;     LAS float* uL = (LAS float*)wl;
;     LAS unsigned char* xb = wl + 4096;
;     {
;         const u32x4* up = (const u32x4*)(U + (tok0 + lane) * 256 + g * 16);
;         const u32x4 w0 = up[0], w1 = up[1];
;         LAS f32x4* d = (LAS f32x4*)(uL + lane * 16);
;         d[0] = (f32x4){bflo(w0.x), bfhi(w0.x), bflo(w0.y), bfhi(w0.y)}; d[1] = (f32x4){bflo(w0.z), bfhi(w0.z), bflo(w0.w), bfhi(w0.w)};
;         d[2] = (f32x4){bflo(w1.x), bfhi(w1.x), bflo(w1.y), bfhi(w1.y)}; d[3] = (f32x4){bflo(w1.z), bfhi(w1.z), bflo(w1.w), bfhi(w1.w)};
;     }
;     const float lr = W.lam_re[g * 64 + lane], li = W.lam_im[g * 64 + lane], dt = __expf(W.log_dt[g]);
;     const float mag = __expf(lr * dt);
;     float sn, cs; { const float ang = li * dt; const float kq = rintf(ang * 0.15915494309189535f); float rr = fmaf(-kq, 6.28125f, ang); rr = fmaf(-kq, 1.9353071795864769e-3f, rr); sn = __sinf(rr); cs = __cosf(rr); }
;     const float ar = mag * cs, ai = mag * sn;
;     const float den = lr * lr + li * li;
;     const float fr = ((ar - 1.f) * lr + ai * li) / den, fi = (ai * lr - (ar - 1.f) * li) / den;
;     float bbr[16], bbi[16];
;     { const f32x4* brp = (const f32x4*)(W.b_re + (size_t)(g * 64 + lane) * 16); const f32x4* bip = (const f32x4*)(W.b_im + (size_t)(g * 64 + lane) * 16);
; #pragma unroll
;       for (int q = 0; q < 4; ++q) { const f32x4 br = brp[q], bi = bip[q];
; #pragma unroll
;           for (int j = 0; j < 4; ++j) { bbr[4 * q + j] = fr * br[j] - fi * bi[j]; bbi[4 * q + j] = fr * bi[j] + fi * br[j]; } } }
.LBB0_434:
	s_ashr_i32 s20, s30, 11
	s_ashr_i32 s21, s20, 31
	s_lshl_b32 s22, s30, 6
	s_bfe_u32 s31, s30, 0x40007
	s_and_b32 s96, s22, 0x1fc0
	s_lshl_b64 s[22:23], s[20:21], 22
	v_lshl_add_u64 v[70:71], s[96:97], 0, v[32:33]
	s_add_u32 s22, s26, s22
	v_lshlrev_b64 v[70:71], 9, v[70:71]
	s_addc_u32 s23, s27, s23
	v_lshl_add_u64 v[70:71], s[22:23], 0, v[70:71]
	s_lshl_b32 s22, s31, 5
	s_mov_b32 s23, s97
	v_lshl_add_u64 v[72:73], v[70:71], 0, s[22:23]
	global_load_dwordx4 v[62:65], v[72:73], off offset:16
	global_load_dwordx4 v[66:69], v[72:73], off
	s_lshl_b32 s21, s31, 2
	s_mov_b64 s[24:25], -1
	v_lshl_add_u32 v74, s31, 6, v32
	v_ashrrev_i32_e32 v75, 31, v74
	v_lshlrev_b64 v[76:77], 2, v[74:75]
	v_lshl_add_u64 v[78:79], s[10:11], 0, v[76:77]
	v_lshl_add_u64 v[76:77], s[12:13], 0, v[76:77]
	global_load_dword v37, v[76:77], off
	v_mov_b32_e32 v80, s21
	global_load_dword v80, v80, s[14:15]
	v_lshlrev_b64 v[74:75], 6, v[74:75]
	global_load_dword v36, v[78:79], off
	v_lshl_add_u64 v[4:5], s[16:17], 0, v[74:75]
	v_lshl_add_u64 v[28:29], s[18:19], 0, v[74:75]
	s_mov_b32 s21, 0
	global_load_dwordx4 v[0:3], v[4:5], off offset:48
	global_load_dwordx4 v[8:11], v[4:5], off offset:32
	global_load_dwordx4 v[16:19], v[4:5], off offset:16
	global_load_dwordx4 v[24:27], v[4:5], off
	s_nop 0
	global_load_dwordx4 v[4:7], v[28:29], off offset:48
	global_load_dwordx4 v[12:15], v[28:29], off offset:32
	global_load_dwordx4 v[20:23], v[28:29], off offset:16
	s_nop 0
	global_load_dwordx4 v[28:31], v[28:29], off
	s_waitcnt vmcnt(11)
	v_lshlrev_b32_e32 v72, 16, v66
	v_and_b32_e32 v73, 0xffff0000, v66
	v_lshlrev_b32_e32 v74, 16, v67
	v_and_b32_e32 v75, 0xffff0000, v67
	ds_write_b128 v41, v[72:75]
	v_lshlrev_b32_e32 v76, 16, v68
	v_and_b32_e32 v77, 0xffff0000, v68
	v_lshlrev_b32_e32 v78, 16, v69
	v_and_b32_e32 v79, 0xffff0000, v69
	ds_write_b128 v41, v[76:79] offset:16
	v_lshlrev_b32_e32 v66, 16, v62
	v_and_b32_e32 v67, 0xffff0000, v62
	v_lshlrev_b32_e32 v68, 16, v63
	v_and_b32_e32 v69, 0xffff0000, v63
	ds_write_b128 v41, v[66:69] offset:32
	v_lshlrev_b32_e32 v72, 16, v64
	v_and_b32_e32 v73, 0xffff0000, v64
	v_lshlrev_b32_e32 v74, 16, v65
	v_and_b32_e32 v75, 0xffff0000, v65
	ds_write_b128 v41, v[72:75] offset:48
	s_waitcnt vmcnt(10)
	v_mov_b32_e32 v40, v37
	s_waitcnt vmcnt(9)
	v_mul_f32_e32 v80, 0x3fb8aa3b, v80
	v_exp_f32_e32 v80, v80
	s_waitcnt vmcnt(8)
	v_pk_mul_f32 v[42:43], v[36:37], v[36:37]
	v_mul_f32_e32 v81, v36, v80
	v_mul_f32_e32 v81, 0x3fb8aa3b, v81
	v_mul_f32_e32 v80, v37, v80
	v_exp_f32_e32 v34, v81
	v_mul_f32_e32 v81, 0.15915494, v80
	v_rndne_f32_e32 v81, v81
	v_fmac_f32_e32 v80, 0xc0c90000, v81
	v_fmac_f32_e32 v80, 0xbafdaa22, v81
	v_mul_f32_e32 v80, 0.15915494, v80
	v_sin_f32_e32 v39, v80
	v_cos_f32_e32 v38, v80
	s_waitcnt lgkmcnt(0)
	v_pk_mul_f32 v[34:35], v[34:35], v[38:39] op_sel_hi:[0,1]
	v_add_f32_e32 v38, -1.0, v34
	v_mov_b32_e32 v39, v35
	v_pk_mul_f32 v[44:45], v[40:41], v[38:39] op_sel:[0,1] op_sel_hi:[0,0]
	v_pk_fma_f32 v[46:47], v[36:37], v[38:39], v[44:45]
	v_pk_fma_f32 v[36:37], v[36:37], v[38:39], v[44:45] op_sel_hi:[0,1,1] neg_lo:[0,0,1] neg_hi:[0,0,1]
	v_pk_add_f32 v[38:39], v[42:43], v[42:43] op_sel:[0,1] op_sel_hi:[0,1]
	v_div_scale_f32 v36, s[22:23], v39, v39, v37
	v_rcp_f32_e32 v40, v36
	s_nop 0
	v_fma_f32 v42, -v36, v40, 1.0
	v_fmac_f32_e32 v40, v42, v40
	v_div_scale_f32 v42, vcc, v37, v39, v37
	v_mul_f32_e32 v43, v42, v40
	v_fma_f32 v44, -v36, v43, v42
	v_fmac_f32_e32 v43, v44, v40
	v_fma_f32 v36, -v36, v43, v42
	v_div_fmas_f32 v36, v36, v40, v43
	v_div_fixup_f32 v39, v36, v39, v37
	v_div_scale_f32 v36, s[22:23], v38, v38, v46
	v_rcp_f32_e32 v37, v36
	s_nop 0
	v_fma_f32 v40, -v36, v37, 1.0
	v_fmac_f32_e32 v37, v40, v37
	v_div_scale_f32 v40, vcc, v46, v38, v46
	v_mul_f32_e32 v42, v40, v37
	v_fma_f32 v43, -v36, v42, v40
	v_fmac_f32_e32 v42, v43, v37
	v_fma_f32 v36, -v36, v42, v40
	v_div_fmas_f32 v36, v36, v37, v42
	v_div_fixup_f32 v38, v36, v38, v46
	s_waitcnt vmcnt(4)
	v_mov_b32_e32 v40, v27
	s_waitcnt vmcnt(0)
; template <bool PASSC>
; __device__ __forceinline__ void ssm_task_old(int task, const SsmW& W, const bf16_t* U, f32x2* SST, bf16_t* YS, LAS unsigned char* wl, int lane) {
;     ...
;     const float ar = mag * cs, ai = mag * sn;
;     const float den = lr * lr + li * li;
;     const float fr = ((ar - 1.f) * lr + ai * li) / den, fi = (ai * lr - (ar - 1.f) * li) / den;
;     float bbr[16], bbi[16];
;     { const f32x4* brp = (const f32x4*)(W.b_re + (size_t)(g * 64 + lane) * 16); const f32x4* bip = (const f32x4*)(W.b_im + (size_t)(g * 64 + lane) * 16);
; #pragma unroll
;       for (int q = 0; q < 4; ++q) { const f32x4 br = brp[q], bi = bip[q];
; #pragma unroll
;           for (int j = 0; j < 4; ++j) { bbr[4 * q + j] = fr * br[j] - fi * bi[j]; bbi[4 * q + j] = fr * bi[j] + fi * br[j]; } } }
	v_pk_mul_f32 v[42:43], v[28:29], v[38:39] op_sel:[0,1] op_sel_hi:[0,0]
	v_pk_fma_f32 v[36:37], v[24:25], v[38:39], v[42:43] neg_lo:[0,0,1] neg_hi:[0,0,1]
	v_pk_fma_f32 v[42:43], v[24:25], v[38:39], v[42:43] op_sel_hi:[0,1,1]
	v_mov_b32_e32 v37, v43
	v_pk_mul_f32 v[42:43], v[28:29], v[38:39] op_sel:[1,1] op_sel_hi:[1,0]
	s_nop 0
	v_pk_fma_f32 v[28:29], v[24:25], v[38:39], v[42:43] op_sel:[1,0,0] neg_lo:[0,0,1] neg_hi:[0,0,1]
	v_pk_fma_f32 v[24:25], v[24:25], v[38:39], v[42:43] op_sel:[1,0,0]
	v_pk_mul_f32 v[42:43], v[30:31], v[38:39] op_sel:[0,1] op_sel_hi:[0,0]
	v_mov_b32_e32 v29, v25
	v_pk_fma_f32 v[24:25], v[26:27], v[38:39], v[42:43] neg_lo:[0,0,1] neg_hi:[0,0,1]
	v_pk_fma_f32 v[42:43], v[26:27], v[38:39], v[42:43] op_sel_hi:[0,1,1]
	v_mov_b32_e32 v26, v31
	v_pk_mul_f32 v[30:31], v[26:27], v[38:39] op_sel:[0,1] op_sel_hi:[0,0]
	v_mov_b32_e32 v25, v43
	v_pk_fma_f32 v[26:27], v[40:41], v[38:39], v[30:31] op_sel_hi:[0,1,1] neg_lo:[0,0,1] neg_hi:[0,0,1]
	v_pk_fma_f32 v[30:31], v[40:41], v[38:39], v[30:31] op_sel_hi:[0,1,1]
	v_pk_mul_f32 v[42:43], v[20:21], v[38:39] op_sel:[0,1] op_sel_hi:[0,0]
	v_mov_b32_e32 v27, v31
	v_pk_fma_f32 v[30:31], v[16:17], v[38:39], v[42:43] neg_lo:[0,0,1] neg_hi:[0,0,1]
	v_pk_fma_f32 v[42:43], v[16:17], v[38:39], v[42:43] op_sel_hi:[0,1,1]
	v_mov_b32_e32 v31, v43
	v_pk_mul_f32 v[42:43], v[20:21], v[38:39] op_sel:[1,1] op_sel_hi:[1,0]
	v_mov_b32_e32 v40, v19
	v_pk_fma_f32 v[20:21], v[16:17], v[38:39], v[42:43] op_sel:[1,0,0] neg_lo:[0,0,1] neg_hi:[0,0,1]
	v_pk_fma_f32 v[16:17], v[16:17], v[38:39], v[42:43] op_sel:[1,0,0]
	v_pk_mul_f32 v[42:43], v[22:23], v[38:39] op_sel:[0,1] op_sel_hi:[0,0]
	v_mov_b32_e32 v21, v17
	v_pk_fma_f32 v[16:17], v[18:19], v[38:39], v[42:43] neg_lo:[0,0,1] neg_hi:[0,0,1]
	v_pk_fma_f32 v[42:43], v[18:19], v[38:39], v[42:43] op_sel_hi:[0,1,1]
	v_mov_b32_e32 v18, v23
	v_pk_mul_f32 v[22:23], v[18:19], v[38:39] op_sel:[0,1] op_sel_hi:[0,0]
	v_mov_b32_e32 v17, v43
	v_pk_fma_f32 v[18:19], v[40:41], v[38:39], v[22:23] op_sel_hi:[0,1,1] neg_lo:[0,0,1] neg_hi:[0,0,1]
	v_pk_fma_f32 v[22:23], v[40:41], v[38:39], v[22:23] op_sel_hi:[0,1,1]
	v_pk_mul_f32 v[42:43], v[12:13], v[38:39] op_sel:[0,1] op_sel_hi:[0,0]
	v_mov_b32_e32 v19, v23
	v_pk_fma_f32 v[22:23], v[8:9], v[38:39], v[42:43] neg_lo:[0,0,1] neg_hi:[0,0,1]
	v_pk_fma_f32 v[42:43], v[8:9], v[38:39], v[42:43] op_sel_hi:[0,1,1]
	v_mov_b32_e32 v23, v43
	v_pk_mul_f32 v[42:43], v[12:13], v[38:39] op_sel:[1,1] op_sel_hi:[1,0]
	v_mov_b32_e32 v40, v11
	v_pk_fma_f32 v[12:13], v[8:9], v[38:39], v[42:43] op_sel:[1,0,0] neg_lo:[0,0,1] neg_hi:[0,0,1]
	v_pk_fma_f32 v[8:9], v[8:9], v[38:39], v[42:43] op_sel:[1,0,0]
	v_pk_mul_f32 v[42:43], v[14:15], v[38:39] op_sel:[0,1] op_sel_hi:[0,0]
	v_mov_b32_e32 v13, v9
	v_pk_fma_f32 v[8:9], v[10:11], v[38:39], v[42:43] neg_lo:[0,0,1] neg_hi:[0,0,1]
	v_pk_fma_f32 v[42:43], v[10:11], v[38:39], v[42:43] op_sel_hi:[0,1,1]
	v_mov_b32_e32 v10, v15
	v_pk_mul_f32 v[14:15], v[10:11], v[38:39] op_sel:[0,1] op_sel_hi:[0,0]
	v_mov_b32_e32 v9, v43
	v_pk_fma_f32 v[10:11], v[40:41], v[38:39], v[14:15] op_sel_hi:[0,1,1] neg_lo:[0,0,1] neg_hi:[0,0,1]
	v_pk_fma_f32 v[14:15], v[40:41], v[38:39], v[14:15] op_sel_hi:[0,1,1]
	v_pk_mul_f32 v[42:43], v[4:5], v[38:39] op_sel:[0,1] op_sel_hi:[0,0]
	v_mov_b32_e32 v11, v15
	v_pk_fma_f32 v[14:15], v[0:1], v[38:39], v[42:43] neg_lo:[0,0,1] neg_hi:[0,0,1]
	v_pk_fma_f32 v[42:43], v[0:1], v[38:39], v[42:43] op_sel_hi:[0,1,1]
	v_mov_b32_e32 v15, v43
	v_pk_mul_f32 v[42:43], v[4:5], v[38:39] op_sel:[1,1] op_sel_hi:[1,0]
	v_mov_b32_e32 v40, v3
	v_pk_fma_f32 v[4:5], v[0:1], v[38:39], v[42:43] op_sel:[1,0,0] neg_lo:[0,0,1] neg_hi:[0,0,1]
	v_pk_fma_f32 v[0:1], v[0:1], v[38:39], v[42:43] op_sel:[1,0,0]
	v_pk_mul_f32 v[42:43], v[6:7], v[38:39] op_sel:[0,1] op_sel_hi:[0,0]
	v_mov_b32_e32 v5, v1
	v_pk_fma_f32 v[0:1], v[2:3], v[38:39], v[42:43] neg_lo:[0,0,1] neg_hi:[0,0,1]
	v_pk_fma_f32 v[42:43], v[2:3], v[38:39], v[42:43] op_sel_hi:[0,1,1]
	v_mov_b32_e32 v2, v7
	v_pk_mul_f32 v[6:7], v[2:3], v[38:39] op_sel:[0,1] op_sel_hi:[0,0]
	v_pk_fma_f32 v[2:3], v[40:41], v[38:39], v[6:7] op_sel_hi:[0,1,1] neg_lo:[0,0,1] neg_hi:[0,0,1]
	v_pk_fma_f32 v[6:7], v[40:41], v[38:39], v[6:7] op_sel_hi:[0,1,1]
	v_mov_b32_e32 v38, 0
	v_mov_b32_e32 v1, v43
	v_mov_b32_e32 v3, v7
	v_pk_mov_b32 v[6:7], v[34:35], v[34:35] op_sel:[1,0]
	v_mov_b32_e32 v39, v38

; #define LAS __attribute__((address_space(3)))
; __device__ __forceinline__ u32x4 pack8(const float* v) { u32x4 w; w.x = cvt_pk_bf16(v[0], v[1]); w.y = cvt_pk_bf16(v[2], v[3]); w.z = cvt_pk_bf16(v[4], v[5]); w.w = cvt_pk_bf16(v[6], v[7]); return w; }
; template <bool PASSC>
; __device__ __forceinline__ void ssm_task(int task, const SsmW& W, const bf16_t* U, f32x2* SST, bf16_t* YS, LAS unsigned char* wl, int lane) {
;     const int g = (task >> 7) & 15, b = task >> 11;
;     const int c = b ? 127 - (task & 127) : (task & 127);
;     const size_t tok0 = (size_t)b * SEQ + c * 64;
;     LAS unsigned char* BU = wl;
;     LAS unsigned char* xb = wl + 8320;
;     const int hh = lane & 15, kq = lane >> 4;
;     const float lr = W.lam_re[g * 64 + lane], li = W.lam_im[g * 64 + lane], dt = __expf(W.log_dt[g]);
;     const float mag = __expf(lr * dt);
;     float sn, cs; { const float ang = li * dt; const float kk = rintf(ang * 0.15915494309189535f); float rr = fmaf(-kk, 6.28125f, ang); rr = fmaf(-kk, 1.9353071795864769e-3f, rr); sn = __sinf(rr); cs = __cosf(rr); }
;     const float ar = mag * cs, ai = mag * sn;
;     const float den = lr * lr + li * li;
;     const float fr = ((ar - 1.f) * lr + ai * li) / den, fi = (ai * lr - (ar - 1.f) * li) / den;
;     {
;         float bbr[16], bbi[16];
;         const f32x4* brp = (const f32x4*)(W.b_re + (size_t)(g * 64 + lane) * 16); const f32x4* bip = (const f32x4*)(W.b_im + (size_t)(g * 64 + lane) * 16);
; #pragma unroll
;         for (int q = 0; q < 4; ++q) { const f32x4 br = brp[q], bi = bip[q];
; #pragma unroll
;             for (int j = 0; j < 4; ++j) { bbr[4 * q + j] = fr * br[j] - fi * bi[j]; bbi[4 * q + j] = fr * bi[j] + fi * br[j]; } }
;         LAS u32x4* t = (LAS u32x4*)(BU + lane * 64);
;         t[0] = pack8(bbr); t[1] = pack8(bbr + 8); t[2] = pack8(bbi); t[3] = pack8(bbi + 8);
;     }
.LBB0_498:
	s_bfe_u32 s49, s48, 0x40007
	v_lshl_add_u32 v100, s49, 6, v64
	v_ashrrev_i32_e32 v101, 31, v100
	v_lshlrev_b64 v[102:103], 2, v[100:101]
	v_lshl_add_u64 v[104:105], s[2:3], 0, v[102:103]
	v_lshl_add_u64 v[102:103], s[34:35], 0, v[102:103]
	s_lshl_b32 s4, s49, 2
	global_load_dword v102, v[102:103], off
	v_mov_b32_e32 v103, s4
	global_load_dword v103, v103, s[36:37]
	v_lshlrev_b64 v[100:101], 6, v[100:101]
	global_load_dword v104, v[104:105], off
	v_lshl_add_u64 v[32:33], s[40:41], 0, v[100:101]
	v_lshl_add_u64 v[2:3], s[38:39], 0, v[100:101]
	global_load_dwordx4 v[4:7], v[2:3], off offset:48
	global_load_dwordx4 v[8:11], v[2:3], off offset:32
	global_load_dwordx4 v[16:19], v[2:3], off offset:16
	global_load_dwordx4 v[24:27], v[2:3], off
	s_nop 0
	global_load_dwordx4 v[0:3], v[32:33], off offset:48
	global_load_dwordx4 v[12:15], v[32:33], off offset:32
	global_load_dwordx4 v[20:23], v[32:33], off offset:16
	s_nop 0
	global_load_dwordx4 v[32:35], v[32:33], off
	s_waitcnt vmcnt(9)
	v_mul_f32_e32 v103, 0x3fb8aa3b, v103
	v_exp_f32_e32 v103, v103
	s_waitcnt vmcnt(8)
	v_mul_f32_e32 v105, v104, v103
	v_mul_f32_e32 v105, 0x3fb8aa3b, v105
	v_mul_f32_e32 v103, v102, v103
	v_exp_f32_e32 v106, v105
	v_mul_f32_e32 v105, 0.15915494, v103
	v_rndne_f32_e32 v105, v105
	v_fmac_f32_e32 v103, 0xc0c90000, v105
	v_fmac_f32_e32 v103, 0xbafdaa22, v105
	v_mul_f32_e32 v103, 0.15915494, v103
	v_sin_f32_e32 v109, v103
	v_cos_f32_e32 v108, v103
	s_nop 0
	v_pk_mul_f32 v[76:77], v[106:107], v[108:109] op_sel_hi:[0,1]
	v_mov_b32_e32 v108, v77
	v_mov_b32_e32 v109, v102
	v_add_f32_e32 v106, -1.0, v76
	v_mov_b32_e32 v107, v104
	v_pk_mul_f32 v[108:109], v[102:103], v[108:109] op_sel_hi:[0,1]
	v_pk_fma_f32 v[108:109], v[104:105], v[106:107], v[108:109] op_sel_hi:[0,1,1]
	v_div_scale_f32 v103, s[4:5], v109, v109, v108
	v_rcp_f32_e32 v105, v103
	v_mul_f32_e32 v102, v102, v106
	v_fma_f32 v102, v104, v77, -v102
	v_mov_b32_e32 v78, v77
	v_fma_f32 v107, -v103, v105, 1.0
	v_fmac_f32_e32 v105, v107, v105
	v_div_scale_f32 v107, vcc, v108, v109, v108
	v_mul_f32_e32 v110, v107, v105
	v_fma_f32 v111, -v103, v110, v107
	v_fmac_f32_e32 v110, v111, v105
	v_fma_f32 v103, -v103, v110, v107
	v_div_fmas_f32 v103, v103, v105, v110
	v_div_fixup_f32 v28, v103, v109, v108
	v_div_scale_f32 v103, s[4:5], v109, v109, v102
	v_rcp_f32_e32 v104, v103
	v_mov_b32_e32 v79, v77
	v_fma_f32 v105, -v103, v104, 1.0
	v_fmac_f32_e32 v104, v105, v104
	v_div_scale_f32 v105, vcc, v102, v109, v102
	v_mul_f32_e32 v106, v105, v104
	v_fma_f32 v107, -v103, v106, v105
	v_fmac_f32_e32 v106, v107, v104
	v_fma_f32 v103, -v103, v106, v105
	v_div_fmas_f32 v103, v103, v104, v106
	v_div_fixup_f32 v30, v103, v109, v102
	s_waitcnt vmcnt(0)
	v_pk_mul_f32 v[36:37], v[32:33], v[30:31] op_sel_hi:[1,0]
	s_nop 0
	v_pk_fma_f32 v[36:37], v[24:25], v[28:29], v[36:37] op_sel_hi:[1,0,1] neg_lo:[0,0,1] neg_hi:[0,0,1]
	v_pk_mul_f32 v[24:25], v[24:25], v[30:31] op_sel_hi:[1,0]
	s_nop 0
	v_pk_fma_f32 v[24:25], v[32:33], v[28:29], v[24:25] op_sel_hi:[1,0,1]
	v_pk_mul_f32 v[32:33], v[34:35], v[30:31] op_sel_hi:[1,0]
	s_nop 0
	v_pk_fma_f32 v[32:33], v[26:27], v[28:29], v[32:33] op_sel_hi:[1,0,1] neg_lo:[0,0,1] neg_hi:[0,0,1]
	v_pk_mul_f32 v[26:27], v[26:27], v[30:31] op_sel_hi:[1,0]
	s_nop 0
	v_pk_fma_f32 v[26:27], v[34:35], v[28:29], v[26:27] op_sel_hi:[1,0,1]
	v_pk_mul_f32 v[34:35], v[20:21], v[30:31] op_sel_hi:[1,0]
	s_nop 0
	v_pk_fma_f32 v[34:35], v[16:17], v[28:29], v[34:35] op_sel_hi:[1,0,1] neg_lo:[0,0,1] neg_hi:[0,0,1]
	v_pk_mul_f32 v[16:17], v[16:17], v[30:31] op_sel_hi:[1,0]
	s_nop 0
	v_pk_fma_f32 v[16:17], v[20:21], v[28:29], v[16:17] op_sel_hi:[1,0,1]
	v_pk_mul_f32 v[20:21], v[22:23], v[30:31] op_sel_hi:[1,0]
	s_nop 0
	v_pk_fma_f32 v[20:21], v[18:19], v[28:29], v[20:21] op_sel_hi:[1,0,1] neg_lo:[0,0,1] neg_hi:[0,0,1]
	v_pk_mul_f32 v[18:19], v[18:19], v[30:31] op_sel_hi:[1,0]
	s_nop 0
	v_pk_fma_f32 v[18:19], v[22:23], v[28:29], v[18:19] op_sel_hi:[1,0,1]
	v_pk_mul_f32 v[22:23], v[12:13], v[30:31] op_sel_hi:[1,0]
	s_nop 0
	v_pk_fma_f32 v[22:23], v[8:9], v[28:29], v[22:23] op_sel_hi:[1,0,1] neg_lo:[0,0,1] neg_hi:[0,0,1]
	v_pk_mul_f32 v[8:9], v[8:9], v[30:31] op_sel_hi:[1,0]
	s_nop 0
	v_pk_fma_f32 v[8:9], v[12:13], v[28:29], v[8:9] op_sel_hi:[1,0,1]
	v_pk_mul_f32 v[12:13], v[14:15], v[30:31] op_sel_hi:[1,0]
	s_nop 0
	v_pk_fma_f32 v[12:13], v[10:11], v[28:29], v[12:13] op_sel_hi:[1,0,1] neg_lo:[0,0,1] neg_hi:[0,0,1]
	v_pk_mul_f32 v[10:11], v[10:11], v[30:31] op_sel_hi:[1,0]
	s_nop 0
	v_pk_fma_f32 v[10:11], v[14:15], v[28:29], v[10:11] op_sel_hi:[1,0,1]
	v_pk_mul_f32 v[14:15], v[0:1], v[30:31] op_sel_hi:[1,0]
	s_nop 0
	v_pk_fma_f32 v[14:15], v[4:5], v[28:29], v[14:15] op_sel_hi:[1,0,1] neg_lo:[0,0,1] neg_hi:[0,0,1]
	v_pk_mul_f32 v[4:5], v[4:5], v[30:31] op_sel_hi:[1,0]
	s_nop 0
	v_pk_fma_f32 v[4:5], v[0:1], v[28:29], v[4:5] op_sel_hi:[1,0,1]
	v_pk_mul_f32 v[0:1], v[2:3], v[30:31] op_sel_hi:[1,0]
	s_nop 0
	v_pk_fma_f32 v[38:39], v[6:7], v[28:29], v[0:1] op_sel_hi:[1,0,1] neg_lo:[0,0,1] neg_hi:[0,0,1]
	v_pk_mul_f32 v[0:1], v[6:7], v[30:31] op_sel_hi:[1,0]
	s_nop 0
	v_pk_fma_f32 v[6:7], v[2:3], v[28:29], v[0:1] op_sel_hi:[1,0,1]
	v_cvt_pk_bf16_f32 v0, v36, v37
	v_cvt_pk_bf16_f32 v1, v32, v33
	v_cvt_pk_bf16_f32 v2, v34, v35
	v_cvt_pk_bf16_f32 v3, v20, v21
	ds_write_b128 v65, v[0:3]
	v_cvt_pk_bf16_f32 v0, v22, v23
	v_cvt_pk_bf16_f32 v1, v12, v13
	v_cvt_pk_bf16_f32 v2, v14, v15
	v_cvt_pk_bf16_f32 v3, v38, v39
	ds_write_b128 v65, v[0:3] offset:16
	v_cvt_pk_bf16_f32 v0, v24, v25
	v_cvt_pk_bf16_f32 v1, v26, v27
	v_cvt_pk_bf16_f32 v2, v16, v17
	v_cvt_pk_bf16_f32 v3, v18, v19
	ds_write_b128 v65, v[0:3] offset:32
	v_cvt_pk_bf16_f32 v0, v8, v9
	v_cvt_pk_bf16_f32 v1, v10, v11
	v_cvt_pk_bf16_f32 v2, v4, v5
	v_cvt_pk_bf16_f32 v3, v6, v7
	ds_write_b128 v65, v[0:3] offset:48
	s_waitcnt lgkmcnt(0)
; #define LAS __attribute__((address_space(3)))
; __device__ __forceinline__ unsigned cvt_pk_bf16(float lo, float hi) { f32x2 v = {lo, hi}; bf16x2_t b = __builtin_convertvector(v, bf16x2_t); return __builtin_bit_cast(unsigned, b); }
; template <bool PASSC>
; __device__ __forceinline__ void ssm_task(int task, const SsmW& W, const bf16_t* U, f32x2* SST, bf16_t* YS, LAS unsigned char* wl, int lane) {
;     ...
;     const bf16x8 zfrag = (bf16x8){0, 0, 0, 0, 0, 0, 0, 0};
;     bf16x8 bfr[8];
; #pragma unroll
;     for (int nb = 0; nb < 8; ++nb) bfr[nb] = (kq < 2) ? *(const LAS bf16x8*)(BU + (16 * nb + hh) * 32 + kq * 16) : zfrag;
;     bf16x8 cf[4];
;     if (PASSC) {
; #pragma unroll
;         for (int ks = 0; ks < 4; ++ks) {
;             const int p0 = 16 * ks + 4 * kq;
;             const f32x4 cre = *(const f32x4*)(W.c_re + (size_t)(g * 16 + hh) * 64 + p0), cim = *(const f32x4*)(W.c_im + (size_t)(g * 16 + hh) * 64 + p0);
;             u32x4 cw; cw.x = cvt_pk_bf16(cre[0], -cim[0]); cw.y = cvt_pk_bf16(cre[1], -cim[1]); cw.z = cvt_pk_bf16(cre[2], -cim[2]); cw.w = cvt_pk_bf16(cre[3], -cim[3]);
;             cf[ks] = __builtin_bit_cast(bf16x8, cw);
;         }
;     }
;     float xr = 0.f, xi = 0.f;
;     if (PASSC) {
;         float tr = ar, ti = ai;
; #pragma unroll
;         for (int i = 0; i < 6; ++i) { const float nr = tr * tr - ti * ti, ni = 2.f * tr * ti; tr = nr; ti = ni; }
;         const f32x2* sp = SST + ((size_t)(b * 16 + g) * 128) * 64 + lane;
;         for (int j0 = 0; j0 < c; j0 += 16) {
	v_mov_b32_e32 v0, 0
	v_mov_b32_e32 v4, 0
	v_mov_b32_e32 v5, 0
	v_mov_b32_e32 v6, 0
	v_mov_b32_e32 v7, 0
	s_and_saveexec_b64 s[4:5], s[0:1]
	ds_read_b128 v[4:7], v124
	s_or_b64 exec, exec, s[4:5]
	v_mov_b32_e32 v1, 0
	v_mov_b32_e32 v2, 0
	v_mov_b32_e32 v3, 0
	s_and_saveexec_b64 s[4:5], s[0:1]
	ds_read_b128 v[0:3], v124 offset:512
	s_or_b64 exec, exec, s[4:5]
	v_mov_b32_e32 v8, 0
	v_mov_b32_e32 v12, 0
	v_mov_b32_e32 v13, 0
	v_mov_b32_e32 v14, 0
	v_mov_b32_e32 v15, 0
	s_and_saveexec_b64 s[4:5], s[0:1]
	ds_read_b128 v[12:15], v124 offset:1024
	s_or_b64 exec, exec, s[4:5]
	v_mov_b32_e32 v9, 0
	v_mov_b32_e32 v10, 0
	v_mov_b32_e32 v11, 0
	s_and_saveexec_b64 s[4:5], s[0:1]
	ds_read_b128 v[8:11], v124 offset:1536
	s_or_b64 exec, exec, s[4:5]
	v_mov_b32_e32 v16, 0
	v_mov_b32_e32 v20, 0
	v_mov_b32_e32 v21, 0
	v_mov_b32_e32 v22, 0
	v_mov_b32_e32 v23, 0
	s_and_saveexec_b64 s[4:5], s[0:1]
	ds_read_b128 v[20:23], v124 offset:2048
	s_or_b64 exec, exec, s[4:5]
	v_mov_b32_e32 v17, 0
	v_mov_b32_e32 v18, 0
	v_mov_b32_e32 v19, 0
	s_and_saveexec_b64 s[4:5], s[0:1]
	ds_read_b128 v[16:19], v124 offset:2560
	s_or_b64 exec, exec, s[4:5]
	v_mov_b32_e32 v24, 0
	v_mov_b32_e32 v28, 0
	v_mov_b32_e32 v29, 0
	v_mov_b32_e32 v30, 0
	v_mov_b32_e32 v31, 0
	s_and_saveexec_b64 s[4:5], s[0:1]
	ds_read_b128 v[28:31], v124 offset:3072
	s_or_b64 exec, exec, s[4:5]
	v_mov_b32_e32 v25, 0
	v_mov_b32_e32 v26, 0
	v_mov_b32_e32 v27, 0
	s_and_saveexec_b64 s[4:5], s[0:1]
	ds_read_b128 v[24:27], v124 offset:3584
	s_or_b64 exec, exec, s[4:5]
	v_lshl_or_b32 v156, s49, 12, v83
	v_lshl_add_u64 v[44:45], v[66:67], 0, v[156:157]
	v_lshl_add_u64 v[48:49], v[68:69], 0, v[156:157]
	global_load_dwordx4 v[32:35], v[44:45], off
	global_load_dwordx4 v[36:39], v[44:45], off offset:64
	global_load_dwordx4 v[60:63], v[48:49], off
	global_load_dwordx4 v[56:59], v[48:49], off offset:64
	global_load_dwordx4 v[40:43], v[44:45], off offset:128
	s_nop 0
	global_load_dwordx4 v[44:47], v[44:45], off offset:192
	s_nop 0
	global_load_dwordx4 v[52:55], v[48:49], off offset:128
	s_nop 0
	global_load_dwordx4 v[48:51], v[48:49], off offset:192
	s_and_b32 s4, s48, 0x7f
	s_lshr_b32 s55, s48, 7
	s_ashr_i32 s46, s48, 11
	s_xor_b32 s5, s4, 0x7f
	s_cmpk_lt_u32 s48, 0x800
	s_cselect_b32 s54, s4, s5
	s_ashr_i32 s47, s46, 31
	s_cmp_eq_u32 s54, 0
	s_cbranch_scc1 .LBB0_547
	v_pk_mul_f32 v[80:81], v[76:77], v[76:77]
	s_lshl_b32 s4, s46, 4
	v_sub_f32_e32 v80, v80, v81
	v_add_f32_e32 v81, v76, v76
	v_mul_f32_e32 v81, v77, v81
	v_mul_f32_e32 v82, v80, v80
	v_add_f32_e32 v80, v80, v80
	v_mul_f32_e32 v80, v81, v80
	v_fma_f32 v82, -v81, v81, v82
	v_mul_f32_e32 v81, v80, v80
	v_fma_f32 v81, v82, v82, -v81
	v_add_f32_e32 v82, v82, v82
	v_mul_f32_e32 v80, v80, v82
	v_mul_f32_e32 v82, v80, v80
	v_fma_f32 v82, v81, v81, -v82
	v_add_f32_e32 v81, v81, v81
	v_mul_f32_e32 v80, v80, v81
	v_mul_f32_e32 v81, v80, v80
	s_and_b32 s5, s55, 15
	v_fma_f32 v84, v82, v82, -v81
	v_add_f32_e32 v81, v82, v82
	s_or_b32 s4, s4, s5
	v_mul_f32_e32 v80, v80, v81
	s_ashr_i32 s5, s4, 31
	v_mul_f32_e32 v81, v80, v80
	v_add_f32_e32 v82, v84, v84
	s_lshl_b64 s[4:5], s[4:5], 16
	v_fma_f32 v81, v84, v84, -v81
	v_mul_f32_e32 v125, v80, v82
	v_lshl_add_u64 v[84:85], v[70:71], 0, s[4:5]
	s_mov_b32 s56, 0
	v_mov_b32_e32 v80, 0
	v_mov_b32_e32 v82, 0
	s_branch .LBB0_517
